# attention unit epilogue: output tile transposed through the dead K/V LDS area, 4 x 16-byte stores per lane instead of 32 x 2-byte
# baseline (speedup 1.0000x reference)
.LBB0_518:
	s_or_b64 exec, exec, s[6:7]
	s_waitcnt lgkmcnt(0)
	v_add_u32_e32 v40, v105, v100
	ds_read_b128 v[32:35], v40 offset:45056
	ds_read_b128 v[36:39], v40 offset:45088
	ds_read_b128 v[42:45], v40 offset:45120
	ds_read_b128 v[46:49], v40 offset:45152
	s_add_i32 s14, s71, s14
	s_lshl_b32 s6, s72, 7
	s_add_u32 s6, s18, s6
	s_addc_u32 s7, s19, 0
	v_mul_u32_u24_e32 v50, 0x90, v102
	v_mul_u32_u24_e32 v51, 0x90, v117
	v_add_u32_e32 v51, v50, v51
	v_lshl_add_u32 v51, v116, 1, v51
	v_lshrrev_b32_e32 v52, 3, v153
	v_and_b32_e32 v53, 7, v153
	v_mul_u32_u24_e32 v54, 0x90, v52
	v_add_u32_e32 v54, v50, v54
	v_lshl_add_u32 v54, v53, 4, v54
	v_add_u32_e32 v55, s14, v102
	v_add_u32_e32 v55, v55, v52
	v_lshlrev_b32_e32 v56, 11, v55
	v_lshl_add_u32 v56, v53, 4, v56
	v_mov_b32_e32 v57, 0
	v_lshl_add_u64 v[56:57], s[6:7], 0, v[56:57]
	s_mov_b64 s[6:7], 0x4000
	v_lshl_add_u64 v[58:59], v[56:57], 0, s[6:7]
	v_lshl_add_u64 v[60:61], v[58:59], 0, s[6:7]
	v_lshl_add_u64 v[62:63], v[60:61], 0, s[6:7]
	s_waitcnt lgkmcnt(0)
	v_mul_f32_e32 v0, v0, v32
	v_mul_f32_e32 v16, v16, v32
	v_cvt_pk_bf16_f32 v0, v0, v16
	ds_write_b16 v51, v0
	ds_write_b16_d16_hi v51, v0 offset:64
	v_mul_f32_e32 v1, v1, v33
	v_mul_f32_e32 v17, v17, v33
	v_cvt_pk_bf16_f32 v1, v1, v17
	ds_write_b16 v51, v1 offset:144
	ds_write_b16_d16_hi v51, v1 offset:208
	v_mul_f32_e32 v2, v2, v34
	v_mul_f32_e32 v18, v18, v34
	v_cvt_pk_bf16_f32 v2, v2, v18
	ds_write_b16 v51, v2 offset:288
	ds_write_b16_d16_hi v51, v2 offset:352
	v_mul_f32_e32 v3, v3, v35
	v_mul_f32_e32 v19, v19, v35
	v_cvt_pk_bf16_f32 v3, v3, v19
	ds_write_b16 v51, v3 offset:432
	ds_write_b16_d16_hi v51, v3 offset:496
	v_mul_f32_e32 v4, v4, v36
	v_mul_f32_e32 v20, v20, v36
	v_cvt_pk_bf16_f32 v4, v4, v20
	ds_write_b16 v51, v4 offset:1152
	ds_write_b16_d16_hi v51, v4 offset:1216
	v_mul_f32_e32 v5, v5, v37
	v_mul_f32_e32 v21, v21, v37
	v_cvt_pk_bf16_f32 v5, v5, v21
	ds_write_b16 v51, v5 offset:1296
	ds_write_b16_d16_hi v51, v5 offset:1360
	v_mul_f32_e32 v6, v6, v38
	v_mul_f32_e32 v22, v22, v38
	v_cvt_pk_bf16_f32 v6, v6, v22
	ds_write_b16 v51, v6 offset:1440
	ds_write_b16_d16_hi v51, v6 offset:1504
	v_mul_f32_e32 v7, v7, v39
	v_mul_f32_e32 v23, v23, v39
	v_cvt_pk_bf16_f32 v7, v7, v23
	ds_write_b16 v51, v7 offset:1584
	ds_write_b16_d16_hi v51, v7 offset:1648
	v_mul_f32_e32 v8, v8, v42
	v_mul_f32_e32 v24, v24, v42
	v_cvt_pk_bf16_f32 v8, v8, v24
	ds_write_b16 v51, v8 offset:2304
	ds_write_b16_d16_hi v51, v8 offset:2368
	v_mul_f32_e32 v9, v9, v43
	v_mul_f32_e32 v25, v25, v43
	v_cvt_pk_bf16_f32 v9, v9, v25
	ds_write_b16 v51, v9 offset:2448
	ds_write_b16_d16_hi v51, v9 offset:2512
	v_mul_f32_e32 v10, v10, v44
	v_mul_f32_e32 v26, v26, v44
	v_cvt_pk_bf16_f32 v10, v10, v26
	ds_write_b16 v51, v10 offset:2592
	ds_write_b16_d16_hi v51, v10 offset:2656
	v_mul_f32_e32 v11, v11, v45
	v_mul_f32_e32 v27, v27, v45
	v_cvt_pk_bf16_f32 v11, v11, v27
	ds_write_b16 v51, v11 offset:2736
	ds_write_b16_d16_hi v51, v11 offset:2800
	v_mul_f32_e32 v12, v12, v46
	v_mul_f32_e32 v28, v28, v46
	v_cvt_pk_bf16_f32 v12, v12, v28
	ds_write_b16 v51, v12 offset:3456
	ds_write_b16_d16_hi v51, v12 offset:3520
	v_mul_f32_e32 v13, v13, v47
	v_mul_f32_e32 v29, v29, v47
	v_cvt_pk_bf16_f32 v13, v13, v29
	ds_write_b16 v51, v13 offset:3600
	ds_write_b16_d16_hi v51, v13 offset:3664
	v_mul_f32_e32 v14, v14, v48
	v_mul_f32_e32 v30, v30, v48
	v_cvt_pk_bf16_f32 v14, v14, v30
	ds_write_b16 v51, v14 offset:3744
	ds_write_b16_d16_hi v51, v14 offset:3808
	v_mul_f32_e32 v15, v15, v49
	v_mul_f32_e32 v31, v31, v49
	v_cvt_pk_bf16_f32 v15, v15, v31
	ds_write_b16 v51, v15 offset:3888
	ds_write_b16_d16_hi v51, v15 offset:3952
	s_waitcnt lgkmcnt(0)
	ds_read_b128 v[0:3], v54
	ds_read_b128 v[4:7], v54 offset:1152
	ds_read_b128 v[8:11], v54 offset:2304
	ds_read_b128 v[12:15], v54 offset:3456
	s_waitcnt lgkmcnt(3)
	global_store_dwordx4 v[56:57], v[0:3], off offset:1024
	s_waitcnt lgkmcnt(2)
	global_store_dwordx4 v[58:59], v[4:7], off offset:1024
	s_waitcnt lgkmcnt(1)
	global_store_dwordx4 v[60:61], v[8:11], off offset:1024
	s_waitcnt lgkmcnt(0)
	global_store_dwordx4 v[62:63], v[12:15], off offset:1024
